# proj epilogue 2: 16-step load/wait ladder replaced by two batches of 8 steps whose gate (z) and previous-term (mrg) loads are issued together; counted waits
# speedup vs baseline: 1.0057x; 1.0005x over previous
.LBB0_548:
	s_or_b64 exec, exec, s[4:5]
	v_mov_b32_e32 v130, v154
	v_mov_b64_e32 v[134:135], s[72:73]
	v_ashrrev_i32_e32 v128, 2, v130
	v_and_b32_e32 v131, 15, v130
	v_and_b32_e32 v128, 0xffffffc0, v128
	v_ashrrev_i32_e32 v129, 31, v128
	v_lshl_or_b32 v136, s12, 8, v131
	v_lshl_add_u64 v[132:133], v[136:137], 0, v[128:129]
	v_lshrrev_b32_e32 v128, 1, v130
	v_and_b32_e32 v128, 0x78, v128
	v_lshl_or_b32 v150, s0, 8, v128
	s_movk_i32 s6, 0x1800
	v_mad_i64_i32 v[144:145], s[0:1], v132, s6, v[134:135]
	s_mov_b64 s[12:13], 0x8d01000
	v_ashrrev_i32_e32 v151, 31, v150
	v_lshl_add_u64 v[148:149], v[144:145], 0, s[12:13]
	v_lshlrev_b64 v[130:131], 1, v[150:151]
	v_lshl_add_u64 v[140:141], v[148:149], 0, v[130:131]
	v_readlane_b32 s4, v254, 19
	v_lshlrev_b64 v[146:147], 11, v[132:133]
	v_readlane_b32 s5, v254, 20
	s_nop 1
	v_lshl_add_u64 v[128:129], s[4:5], 0, v[146:147]
	v_lshl_add_u64 v[128:129], v[128:129], 0, v[130:131]
	v_lshl_add_u64 v[242:243], v[144:145], 0, v[130:131]
	v_mov_b64_e32 v[246:247], v[128:129]
	s_mov_b64 s[92:93], 0x8d01000
	v_lshl_add_u64 v[244:245], v[242:243], 0, s[92:93]
	global_load_dwordx4 v[178:181], v[244:245], off
	s_mov_b64 s[92:93], 0x0
	v_lshl_add_u64 v[248:249], v[246:247], 0, s[92:93]
	global_load_dwordx4 v[182:185], v[248:249], off
	s_mov_b64 s[92:93], 0x8d01100
	v_lshl_add_u64 v[244:245], v[242:243], 0, s[92:93]
	global_load_dwordx4 v[186:189], v[244:245], off
	s_mov_b64 s[92:93], 0x100
	v_lshl_add_u64 v[248:249], v[246:247], 0, s[92:93]
	global_load_dwordx4 v[190:193], v[248:249], off
	s_mov_b64 s[92:93], 0x8d19000
	v_lshl_add_u64 v[244:245], v[242:243], 0, s[92:93]
	global_load_dwordx4 v[194:197], v[244:245], off
	s_mov_b64 s[92:93], 0x8000
	v_lshl_add_u64 v[248:249], v[246:247], 0, s[92:93]
	global_load_dwordx4 v[198:201], v[248:249], off
	s_mov_b64 s[92:93], 0x8d19100
	v_lshl_add_u64 v[244:245], v[242:243], 0, s[92:93]
	global_load_dwordx4 v[202:205], v[244:245], off
	s_mov_b64 s[92:93], 0x8100
	v_lshl_add_u64 v[248:249], v[246:247], 0, s[92:93]
	global_load_dwordx4 v[206:209], v[248:249], off
	s_mov_b64 s[92:93], 0x8d31000
	v_lshl_add_u64 v[244:245], v[242:243], 0, s[92:93]
	global_load_dwordx4 v[210:213], v[244:245], off
	s_mov_b64 s[92:93], 0x10000
	v_lshl_add_u64 v[248:249], v[246:247], 0, s[92:93]
	global_load_dwordx4 v[214:217], v[248:249], off
	s_mov_b64 s[92:93], 0x8d31100
	v_lshl_add_u64 v[244:245], v[242:243], 0, s[92:93]
	global_load_dwordx4 v[218:221], v[244:245], off
	s_mov_b64 s[92:93], 0x10100
	v_lshl_add_u64 v[248:249], v[246:247], 0, s[92:93]
	global_load_dwordx4 v[222:225], v[248:249], off
	s_mov_b64 s[92:93], 0x8d49000
	v_lshl_add_u64 v[244:245], v[242:243], 0, s[92:93]
	global_load_dwordx4 v[226:229], v[244:245], off
	s_mov_b64 s[92:93], 0x18000
	v_lshl_add_u64 v[248:249], v[246:247], 0, s[92:93]
	global_load_dwordx4 v[230:233], v[248:249], off
	s_mov_b64 s[92:93], 0x8d49100
	v_lshl_add_u64 v[244:245], v[242:243], 0, s[92:93]
	global_load_dwordx4 v[234:237], v[244:245], off
	s_mov_b64 s[92:93], 0x18100
	v_lshl_add_u64 v[248:249], v[246:247], 0, s[92:93]
	global_load_dwordx4 v[238:241], v[248:249], off
	s_waitcnt vmcnt(14)
	v_lshlrev_b32_e32 v136, 16, v178
	v_mul_f32_e32 v136, 0xbfb8aa3b, v136
	v_exp_f32_e32 v136, v136
	v_and_b32_e32 v139, 0xffff0000, v178
	v_lshlrev_b32_e32 v151, 16, v179
	v_and_b32_e32 v152, 0xffff0000, v179
	v_add_f32_e32 v136, 1.0, v136
	v_rcp_f32_e32 v140, v136
	v_mul_f32_e32 v136, 0xbfb8aa3b, v139
	v_exp_f32_e32 v136, v136
	v_lshlrev_b32_e32 v153, 16, v180
	v_and_b32_e32 v170, 0xffff0000, v180
	v_lshlrev_b32_e32 v171, 16, v181
	v_add_f32_e32 v136, 1.0, v136
	v_rcp_f32_e32 v141, v136
	v_mul_f32_e32 v136, 0xbfb8aa3b, v151
	v_exp_f32_e32 v136, v136
	v_and_b32_e32 v172, 0xffff0000, v181
	v_lshlrev_b32_e32 v142, 16, v182
	v_and_b32_e32 v143, 0xffff0000, v182
	v_add_f32_e32 v136, 1.0, v136
	v_pk_fma_f32 v[124:125], v[124:125], v[140:141], v[142:143]
	v_rcp_f32_e32 v140, v136
	v_mul_f32_e32 v136, 0xbfb8aa3b, v152
	v_exp_f32_e32 v136, v136
	v_lshlrev_b32_e32 v142, 16, v183
	v_and_b32_e32 v143, 0xffff0000, v183
	v_add_f32_e32 v136, 1.0, v136
	v_rcp_f32_e32 v141, v136
	v_mul_f32_e32 v136, 0xbfb8aa3b, v153
	v_exp_f32_e32 v136, v136
	v_pk_fma_f32 v[126:127], v[126:127], v[140:141], v[142:143]
	v_lshlrev_b32_e32 v142, 16, v184
	v_add_f32_e32 v136, 1.0, v136
	v_rcp_f32_e32 v140, v136
	v_mul_f32_e32 v136, 0xbfb8aa3b, v170
	v_exp_f32_e32 v136, v136
	v_and_b32_e32 v143, 0xffff0000, v184
	v_add_f32_e32 v136, 1.0, v136
	v_rcp_f32_e32 v141, v136
	s_nop 0
	v_pk_fma_f32 v[140:141], v[120:121], v[140:141], v[142:143]
	v_mul_f32_e32 v120, 0xbfb8aa3b, v171
	v_mul_f32_e32 v121, 0xbfb8aa3b, v172
	v_exp_f32_e32 v120, v120
	v_exp_f32_e32 v121, v121
	v_lshlrev_b32_e32 v142, 16, v185
	v_and_b32_e32 v143, 0xffff0000, v185
	v_add_f32_e32 v120, 1.0, v120
	v_add_f32_e32 v121, 1.0, v121
	v_rcp_f32_e32 v120, v120
	v_rcp_f32_e32 v121, v121
	s_nop 0
	v_pk_fma_f32 v[142:143], v[122:123], v[120:121], v[142:143]
	v_cvt_pk_bf16_f32 v120, v124, v125
	v_cvt_pk_bf16_f32 v121, v126, v127
	v_cvt_pk_bf16_f32 v122, v140, v141
	v_cvt_pk_bf16_f32 v123, v142, v143
	global_store_dwordx4 v[128:129], v[120:123], off
	s_nop 1
	v_or_b32_e32 v120, 0x80, v150
	v_ashrrev_i32_e32 v121, 31, v120
	v_lshlrev_b64 v[124:125], 1, v[120:121]
	v_lshl_add_u64 v[120:121], v[148:149], 0, v[124:125]
	s_nop 0
	s_waitcnt vmcnt(13)
	v_lshlrev_b32_e32 v126, 16, v186
	v_and_b32_e32 v127, 0xffff0000, v186
	v_mul_f32_e32 v126, 0xbfb8aa3b, v126
	v_mul_f32_e32 v127, 0xbfb8aa3b, v127
	v_exp_f32_e32 v126, v126
	v_exp_f32_e32 v127, v127
	v_lshlrev_b32_e32 v136, 16, v187
	v_and_b32_e32 v139, 0xffff0000, v187
	s_waitcnt vmcnt(13)
	v_lshlrev_b32_e32 v140, 16, v190
	v_and_b32_e32 v141, 0xffff0000, v190
	v_mul_f32_e32 v120, 0xbfb8aa3b, v136
	v_add_f32_e32 v126, 1.0, v126
	v_add_f32_e32 v127, 1.0, v127
	v_exp_f32_e32 v120, v120
	v_rcp_f32_e32 v126, v126
	v_rcp_f32_e32 v127, v127
	v_lshlrev_b32_e32 v148, 16, v188
	v_add_f32_e32 v120, 1.0, v120
	v_and_b32_e32 v142, 0xffff0000, v188
	v_pk_fma_f32 v[116:117], v[116:117], v[126:127], v[140:141]
	v_rcp_f32_e32 v126, v120
	v_mul_f32_e32 v120, 0xbfb8aa3b, v139
	v_exp_f32_e32 v120, v120
	v_lshlrev_b32_e32 v149, 16, v189
	v_and_b32_e32 v143, 0xffff0000, v189
	v_add_f32_e32 v120, 1.0, v120
	v_rcp_f32_e32 v127, v120
	v_lshlrev_b32_e32 v120, 16, v191
	v_and_b32_e32 v121, 0xffff0000, v191
	v_pk_fma_f32 v[118:119], v[118:119], v[126:127], v[120:121]
	v_mul_f32_e32 v120, 0xbfb8aa3b, v148
	v_mul_f32_e32 v121, 0xbfb8aa3b, v142
	v_exp_f32_e32 v120, v120
	v_exp_f32_e32 v121, v121
	v_lshlrev_b32_e32 v126, 16, v192
	v_and_b32_e32 v127, 0xffff0000, v192
	v_add_f32_e32 v120, 1.0, v120
	v_add_f32_e32 v121, 1.0, v121
	v_rcp_f32_e32 v120, v120
	v_rcp_f32_e32 v121, v121
	v_lshlrev_b32_e32 v122, 16, v193
	v_and_b32_e32 v123, 0xffff0000, v193
	v_pk_fma_f32 v[120:121], v[112:113], v[120:121], v[126:127]
	v_mul_f32_e32 v112, 0xbfb8aa3b, v149
	v_mul_f32_e32 v113, 0xbfb8aa3b, v143
	v_exp_f32_e32 v112, v112
	v_exp_f32_e32 v113, v113
	v_add_f32_e32 v112, 1.0, v112
	v_add_f32_e32 v113, 1.0, v113
	v_rcp_f32_e32 v112, v112
	v_rcp_f32_e32 v113, v113
	s_nop 0
	v_pk_fma_f32 v[122:123], v[114:115], v[112:113], v[122:123]
	v_cvt_pk_bf16_f32 v112, v116, v117
	v_cvt_pk_bf16_f32 v113, v118, v119
	v_cvt_pk_bf16_f32 v114, v120, v121
	v_cvt_pk_bf16_f32 v115, v122, v123
	global_store_dwordx4 v[128:129], v[112:115], off offset:256
	s_mov_b64 s[14:15], 0x8d19000
	s_nop 0
	v_lshl_add_u64 v[114:115], v[144:145], 0, s[14:15]
	v_lshl_add_u64 v[116:117], v[114:115], 0, v[130:131]
	v_or_b32_e32 v112, 0x8000, v146
	v_mov_b32_e32 v113, v147
	v_lshl_add_u64 v[112:113], s[4:5], 0, v[112:113]
	v_lshl_add_u64 v[112:113], v[112:113], 0, v[130:131]
	s_waitcnt vmcnt(12)
	v_lshlrev_b32_e32 v126, 16, v194
	v_and_b32_e32 v127, 0xffff0000, v194
	v_lshlrev_b32_e32 v136, 16, v195
	v_and_b32_e32 v139, 0xffff0000, v195
	v_mul_f32_e32 v116, 0xbfb8aa3b, v126
	v_mul_f32_e32 v117, 0xbfb8aa3b, v127
	v_exp_f32_e32 v116, v116
	v_exp_f32_e32 v117, v117
	v_lshlrev_b32_e32 v140, 16, v196
	v_and_b32_e32 v141, 0xffff0000, v196
	v_add_f32_e32 v116, 1.0, v116
	v_add_f32_e32 v117, 1.0, v117
	v_rcp_f32_e32 v116, v116
	v_rcp_f32_e32 v117, v117
	v_lshlrev_b32_e32 v142, 16, v197
	v_and_b32_e32 v143, 0xffff0000, v197
	s_waitcnt vmcnt(12)
	v_lshlrev_b32_e32 v118, 16, v198
	v_and_b32_e32 v119, 0xffff0000, v198
	v_pk_fma_f32 v[108:109], v[108:109], v[116:117], v[118:119]
	v_mul_f32_e32 v116, 0xbfb8aa3b, v136
	v_mul_f32_e32 v117, 0xbfb8aa3b, v139
	v_exp_f32_e32 v116, v116
	v_exp_f32_e32 v117, v117
	v_lshlrev_b32_e32 v118, 16, v199
	v_and_b32_e32 v119, 0xffff0000, v199
	v_add_f32_e32 v116, 1.0, v116
	v_add_f32_e32 v117, 1.0, v117
	v_rcp_f32_e32 v116, v116
	v_rcp_f32_e32 v117, v117
	s_nop 0
	v_pk_fma_f32 v[110:111], v[110:111], v[116:117], v[118:119]
	v_mul_f32_e32 v116, 0xbfb8aa3b, v140
	v_mul_f32_e32 v117, 0xbfb8aa3b, v141
	v_exp_f32_e32 v116, v116
	v_exp_f32_e32 v117, v117
	v_lshlrev_b32_e32 v118, 16, v200
	v_and_b32_e32 v119, 0xffff0000, v200
	v_add_f32_e32 v116, 1.0, v116
	v_add_f32_e32 v117, 1.0, v117
	v_rcp_f32_e32 v116, v116
	v_rcp_f32_e32 v117, v117
	s_nop 0
	v_pk_fma_f32 v[116:117], v[104:105], v[116:117], v[118:119]
	v_mul_f32_e32 v104, 0xbfb8aa3b, v142
	v_mul_f32_e32 v105, 0xbfb8aa3b, v143
	v_exp_f32_e32 v104, v104
	v_exp_f32_e32 v105, v105
	v_lshlrev_b32_e32 v118, 16, v201
	v_and_b32_e32 v119, 0xffff0000, v201
	v_add_f32_e32 v104, 1.0, v104
	v_add_f32_e32 v105, 1.0, v105
	v_rcp_f32_e32 v104, v104
	v_rcp_f32_e32 v105, v105
	s_nop 0
	v_pk_fma_f32 v[118:119], v[106:107], v[104:105], v[118:119]
	v_cvt_pk_bf16_f32 v104, v108, v109
	v_cvt_pk_bf16_f32 v105, v110, v111
	v_cvt_pk_bf16_f32 v106, v116, v117
	v_cvt_pk_bf16_f32 v107, v118, v119
	global_store_dwordx4 v[112:113], v[104:107], off
	s_nop 1
	v_lshl_add_u64 v[104:105], v[114:115], 0, v[124:125]
	s_nop 0
	s_waitcnt vmcnt(11)
	v_lshlrev_b32_e32 v114, 16, v202
	v_and_b32_e32 v115, 0xffff0000, v202
	v_lshlrev_b32_e32 v116, 16, v203
	v_and_b32_e32 v117, 0xffff0000, v203
	v_mul_f32_e32 v108, 0xbfb8aa3b, v114
	v_mul_f32_e32 v109, 0xbfb8aa3b, v115
	v_exp_f32_e32 v108, v108
	v_exp_f32_e32 v109, v109
	v_lshlrev_b32_e32 v118, 16, v204
	v_and_b32_e32 v119, 0xffff0000, v204
	v_lshlrev_b32_e32 v120, 16, v205
	v_and_b32_e32 v121, 0xffff0000, v205
	s_waitcnt vmcnt(11)
	v_lshlrev_b32_e32 v110, 16, v206
	v_and_b32_e32 v111, 0xffff0000, v206
	v_mul_f32_e32 v104, 0xbfb8aa3b, v116
	v_add_f32_e32 v108, 1.0, v108
	v_add_f32_e32 v109, 1.0, v109
	v_exp_f32_e32 v104, v104
	v_rcp_f32_e32 v108, v108
	v_rcp_f32_e32 v109, v109
	v_add_f32_e32 v104, 1.0, v104
	v_pk_fma_f32 v[100:101], v[100:101], v[108:109], v[110:111]
	v_rcp_f32_e32 v108, v104
	v_mul_f32_e32 v104, 0xbfb8aa3b, v117
	v_exp_f32_e32 v104, v104
	s_nop 0
	v_add_f32_e32 v104, 1.0, v104
	v_rcp_f32_e32 v109, v104
	v_lshlrev_b32_e32 v104, 16, v207
	v_and_b32_e32 v105, 0xffff0000, v207
	v_pk_fma_f32 v[102:103], v[102:103], v[108:109], v[104:105]
	v_mul_f32_e32 v104, 0xbfb8aa3b, v118
	v_mul_f32_e32 v105, 0xbfb8aa3b, v119
	v_exp_f32_e32 v104, v104
	v_exp_f32_e32 v105, v105
	v_lshlrev_b32_e32 v108, 16, v208
	v_and_b32_e32 v109, 0xffff0000, v208
	v_add_f32_e32 v104, 1.0, v104
	v_add_f32_e32 v105, 1.0, v105
	v_rcp_f32_e32 v104, v104
	v_rcp_f32_e32 v105, v105
	v_lshlrev_b32_e32 v106, 16, v209
	v_and_b32_e32 v107, 0xffff0000, v209
	v_pk_fma_f32 v[104:105], v[96:97], v[104:105], v[108:109]
	v_mul_f32_e32 v96, 0xbfb8aa3b, v120
	v_mul_f32_e32 v97, 0xbfb8aa3b, v121
	v_exp_f32_e32 v96, v96
	v_exp_f32_e32 v97, v97
	v_add_f32_e32 v96, 1.0, v96
	v_add_f32_e32 v97, 1.0, v97
	v_rcp_f32_e32 v96, v96
	v_rcp_f32_e32 v97, v97
	s_nop 0
	v_pk_fma_f32 v[106:107], v[98:99], v[96:97], v[106:107]
	v_cvt_pk_bf16_f32 v96, v100, v101
	v_cvt_pk_bf16_f32 v97, v102, v103
	v_cvt_pk_bf16_f32 v98, v104, v105
	v_cvt_pk_bf16_f32 v99, v106, v107
	global_store_dwordx4 v[112:113], v[96:99], off offset:256
	s_mov_b64 s[36:37], 0x8d31000
	s_nop 0
	v_lshl_add_u64 v[98:99], v[144:145], 0, s[36:37]
	v_lshl_add_u64 v[100:101], v[98:99], 0, v[130:131]
	v_or_b32_e32 v96, 0x10000, v146
	v_mov_b32_e32 v97, v147
	v_lshl_add_u64 v[96:97], s[4:5], 0, v[96:97]
	v_lshl_add_u64 v[96:97], v[96:97], 0, v[130:131]
	s_waitcnt vmcnt(10)
	v_lshlrev_b32_e32 v108, 16, v210
	v_and_b32_e32 v109, 0xffff0000, v210
	v_lshlrev_b32_e32 v110, 16, v211
	v_and_b32_e32 v111, 0xffff0000, v211
	v_mul_f32_e32 v100, 0xbfb8aa3b, v108
	v_mul_f32_e32 v101, 0xbfb8aa3b, v109
	v_exp_f32_e32 v100, v100
	v_exp_f32_e32 v101, v101
	v_lshlrev_b32_e32 v112, 16, v212
	v_and_b32_e32 v113, 0xffff0000, v212
	v_add_f32_e32 v100, 1.0, v100
	v_add_f32_e32 v101, 1.0, v101
	v_rcp_f32_e32 v100, v100
	v_rcp_f32_e32 v101, v101
	v_lshlrev_b32_e32 v114, 16, v213
	v_and_b32_e32 v115, 0xffff0000, v213
	s_waitcnt vmcnt(10)
	v_lshlrev_b32_e32 v102, 16, v214
	v_and_b32_e32 v103, 0xffff0000, v214
	v_pk_fma_f32 v[92:93], v[92:93], v[100:101], v[102:103]
	v_mul_f32_e32 v100, 0xbfb8aa3b, v110
	v_mul_f32_e32 v101, 0xbfb8aa3b, v111
	v_exp_f32_e32 v100, v100
	v_exp_f32_e32 v101, v101
	v_lshlrev_b32_e32 v102, 16, v215
	v_and_b32_e32 v103, 0xffff0000, v215
	v_add_f32_e32 v100, 1.0, v100
	v_add_f32_e32 v101, 1.0, v101
	v_rcp_f32_e32 v100, v100
	v_rcp_f32_e32 v101, v101
	s_nop 0
	v_pk_fma_f32 v[94:95], v[94:95], v[100:101], v[102:103]
	v_mul_f32_e32 v100, 0xbfb8aa3b, v112
	v_mul_f32_e32 v101, 0xbfb8aa3b, v113
	v_exp_f32_e32 v100, v100
	v_exp_f32_e32 v101, v101
	v_lshlrev_b32_e32 v102, 16, v216
	v_and_b32_e32 v103, 0xffff0000, v216
	v_add_f32_e32 v100, 1.0, v100
	v_add_f32_e32 v101, 1.0, v101
	v_rcp_f32_e32 v100, v100
	v_rcp_f32_e32 v101, v101
	s_nop 0
	v_pk_fma_f32 v[100:101], v[88:89], v[100:101], v[102:103]
	v_mul_f32_e32 v88, 0xbfb8aa3b, v114
	v_mul_f32_e32 v89, 0xbfb8aa3b, v115
	v_exp_f32_e32 v88, v88
	v_exp_f32_e32 v89, v89
	v_lshlrev_b32_e32 v102, 16, v217
	v_and_b32_e32 v103, 0xffff0000, v217
	v_add_f32_e32 v88, 1.0, v88
	v_add_f32_e32 v89, 1.0, v89
	v_rcp_f32_e32 v88, v88
	v_rcp_f32_e32 v89, v89
	s_nop 0
	v_pk_fma_f32 v[102:103], v[90:91], v[88:89], v[102:103]
	v_cvt_pk_bf16_f32 v88, v92, v93
	v_cvt_pk_bf16_f32 v89, v94, v95
	v_cvt_pk_bf16_f32 v90, v100, v101
	v_cvt_pk_bf16_f32 v91, v102, v103
	global_store_dwordx4 v[96:97], v[88:91], off
	s_nop 1
	v_lshl_add_u64 v[88:89], v[98:99], 0, v[124:125]
	s_nop 0
	s_waitcnt vmcnt(9)
	v_lshlrev_b32_e32 v98, 16, v218
	v_and_b32_e32 v99, 0xffff0000, v218
	v_lshlrev_b32_e32 v100, 16, v219
	v_and_b32_e32 v101, 0xffff0000, v219
	v_mul_f32_e32 v92, 0xbfb8aa3b, v98
	v_mul_f32_e32 v93, 0xbfb8aa3b, v99
	v_exp_f32_e32 v92, v92
	v_exp_f32_e32 v93, v93
	v_lshlrev_b32_e32 v102, 16, v220
	v_and_b32_e32 v103, 0xffff0000, v220
	v_lshlrev_b32_e32 v104, 16, v221
	v_and_b32_e32 v105, 0xffff0000, v221
	s_waitcnt vmcnt(9)
	v_lshlrev_b32_e32 v94, 16, v222
	v_and_b32_e32 v95, 0xffff0000, v222
	v_mul_f32_e32 v88, 0xbfb8aa3b, v100
	v_add_f32_e32 v92, 1.0, v92
	v_add_f32_e32 v93, 1.0, v93
	v_exp_f32_e32 v88, v88
	v_rcp_f32_e32 v92, v92
	v_rcp_f32_e32 v93, v93
	v_add_f32_e32 v88, 1.0, v88
	v_pk_fma_f32 v[84:85], v[84:85], v[92:93], v[94:95]
	v_rcp_f32_e32 v92, v88
	v_mul_f32_e32 v88, 0xbfb8aa3b, v101
	v_exp_f32_e32 v88, v88
	s_nop 0
	v_add_f32_e32 v88, 1.0, v88
	v_rcp_f32_e32 v93, v88
	v_lshlrev_b32_e32 v88, 16, v223
	v_and_b32_e32 v89, 0xffff0000, v223
	v_pk_fma_f32 v[86:87], v[86:87], v[92:93], v[88:89]
	v_mul_f32_e32 v88, 0xbfb8aa3b, v102
	v_mul_f32_e32 v89, 0xbfb8aa3b, v103
	v_exp_f32_e32 v88, v88
	v_exp_f32_e32 v89, v89
	v_lshlrev_b32_e32 v92, 16, v224
	v_and_b32_e32 v93, 0xffff0000, v224
	v_add_f32_e32 v88, 1.0, v88
	v_add_f32_e32 v89, 1.0, v89
	v_rcp_f32_e32 v88, v88
	v_rcp_f32_e32 v89, v89
	v_lshlrev_b32_e32 v90, 16, v225
	v_and_b32_e32 v91, 0xffff0000, v225
	v_pk_fma_f32 v[88:89], v[80:81], v[88:89], v[92:93]
	v_mul_f32_e32 v80, 0xbfb8aa3b, v104
	v_mul_f32_e32 v81, 0xbfb8aa3b, v105
	v_exp_f32_e32 v80, v80
	v_exp_f32_e32 v81, v81
	v_add_f32_e32 v80, 1.0, v80
	v_add_f32_e32 v81, 1.0, v81
	v_rcp_f32_e32 v80, v80
	v_rcp_f32_e32 v81, v81
	s_nop 0
	v_pk_fma_f32 v[90:91], v[82:83], v[80:81], v[90:91]
	v_cvt_pk_bf16_f32 v80, v84, v85
	v_cvt_pk_bf16_f32 v81, v86, v87
	v_cvt_pk_bf16_f32 v82, v88, v89
	v_cvt_pk_bf16_f32 v83, v90, v91
	global_store_dwordx4 v[96:97], v[80:83], off offset:256
	s_mov_b64 s[0:1], 0x8d49000
	s_nop 0
	v_lshl_add_u64 v[82:83], v[144:145], 0, s[0:1]
	v_lshl_add_u64 v[84:85], v[82:83], 0, v[130:131]
	v_or_b32_e32 v146, 0x18000, v146
	v_lshl_add_u64 v[80:81], s[4:5], 0, v[146:147]
	v_lshl_add_u64 v[80:81], v[80:81], 0, v[130:131]
	s_waitcnt vmcnt(8)
	v_lshlrev_b32_e32 v92, 16, v226
	v_and_b32_e32 v93, 0xffff0000, v226
	v_lshlrev_b32_e32 v94, 16, v227
	v_and_b32_e32 v95, 0xffff0000, v227
	v_mul_f32_e32 v84, 0xbfb8aa3b, v92
	v_mul_f32_e32 v85, 0xbfb8aa3b, v93
	v_exp_f32_e32 v84, v84
	v_exp_f32_e32 v85, v85
	v_lshlrev_b32_e32 v96, 16, v228
	v_and_b32_e32 v97, 0xffff0000, v228
	v_add_f32_e32 v84, 1.0, v84
	v_add_f32_e32 v85, 1.0, v85
	v_rcp_f32_e32 v84, v84
	v_rcp_f32_e32 v85, v85
	v_lshlrev_b32_e32 v98, 16, v229
	v_and_b32_e32 v99, 0xffff0000, v229
	s_waitcnt vmcnt(8)
	v_lshlrev_b32_e32 v86, 16, v230
	v_and_b32_e32 v87, 0xffff0000, v230
	v_pk_fma_f32 v[76:77], v[76:77], v[84:85], v[86:87]
	v_mul_f32_e32 v84, 0xbfb8aa3b, v94
	v_mul_f32_e32 v85, 0xbfb8aa3b, v95
	v_exp_f32_e32 v84, v84
	v_exp_f32_e32 v85, v85
	v_lshlrev_b32_e32 v86, 16, v231
	v_and_b32_e32 v87, 0xffff0000, v231
	v_add_f32_e32 v84, 1.0, v84
	v_add_f32_e32 v85, 1.0, v85
	v_rcp_f32_e32 v84, v84
	v_rcp_f32_e32 v85, v85
	s_nop 0
	v_pk_fma_f32 v[78:79], v[78:79], v[84:85], v[86:87]
	v_mul_f32_e32 v84, 0xbfb8aa3b, v96
	v_mul_f32_e32 v85, 0xbfb8aa3b, v97
	v_exp_f32_e32 v84, v84
	v_exp_f32_e32 v85, v85
	v_lshlrev_b32_e32 v86, 16, v232
	v_and_b32_e32 v87, 0xffff0000, v232
	v_add_f32_e32 v84, 1.0, v84
	v_add_f32_e32 v85, 1.0, v85
	v_rcp_f32_e32 v84, v84
	v_rcp_f32_e32 v85, v85
	s_nop 0
	v_pk_fma_f32 v[84:85], v[72:73], v[84:85], v[86:87]
	v_mul_f32_e32 v72, 0xbfb8aa3b, v98
	v_mul_f32_e32 v73, 0xbfb8aa3b, v99
	v_exp_f32_e32 v72, v72
	v_exp_f32_e32 v73, v73
	v_lshlrev_b32_e32 v86, 16, v233
	v_and_b32_e32 v87, 0xffff0000, v233
	v_add_f32_e32 v72, 1.0, v72
	v_add_f32_e32 v73, 1.0, v73
	v_rcp_f32_e32 v72, v72
	v_rcp_f32_e32 v73, v73
	s_nop 0
	v_pk_fma_f32 v[86:87], v[74:75], v[72:73], v[86:87]
	v_cvt_pk_bf16_f32 v72, v76, v77
	v_cvt_pk_bf16_f32 v73, v78, v79
	v_cvt_pk_bf16_f32 v74, v84, v85
	v_cvt_pk_bf16_f32 v75, v86, v87
	global_store_dwordx4 v[80:81], v[72:75], off
	s_nop 1
	v_lshl_add_u64 v[72:73], v[82:83], 0, v[124:125]
	s_nop 0
	s_waitcnt vmcnt(7)
	v_lshlrev_b32_e32 v82, 16, v234
	v_and_b32_e32 v83, 0xffff0000, v234
	v_lshlrev_b32_e32 v84, 16, v235
	v_and_b32_e32 v85, 0xffff0000, v235
	v_mul_f32_e32 v76, 0xbfb8aa3b, v82
	v_mul_f32_e32 v77, 0xbfb8aa3b, v83
	v_exp_f32_e32 v76, v76
	v_exp_f32_e32 v77, v77
	v_lshlrev_b32_e32 v86, 16, v236
	v_and_b32_e32 v87, 0xffff0000, v236
	v_lshlrev_b32_e32 v88, 16, v237
	v_and_b32_e32 v89, 0xffff0000, v237
	s_waitcnt vmcnt(7)
	v_lshlrev_b32_e32 v78, 16, v238
	v_and_b32_e32 v79, 0xffff0000, v238
	v_mul_f32_e32 v72, 0xbfb8aa3b, v84
	v_add_f32_e32 v76, 1.0, v76
	v_add_f32_e32 v77, 1.0, v77
	v_exp_f32_e32 v72, v72
	v_rcp_f32_e32 v76, v76
	v_rcp_f32_e32 v77, v77
	v_add_f32_e32 v72, 1.0, v72
	v_pk_fma_f32 v[68:69], v[68:69], v[76:77], v[78:79]
	v_rcp_f32_e32 v76, v72
	v_mul_f32_e32 v72, 0xbfb8aa3b, v85
	v_exp_f32_e32 v72, v72
	s_nop 0
	v_add_f32_e32 v72, 1.0, v72
	v_rcp_f32_e32 v77, v72
	v_lshlrev_b32_e32 v72, 16, v239
	v_and_b32_e32 v73, 0xffff0000, v239
	v_pk_fma_f32 v[70:71], v[70:71], v[76:77], v[72:73]
	v_mul_f32_e32 v72, 0xbfb8aa3b, v86
	v_mul_f32_e32 v73, 0xbfb8aa3b, v87
	v_exp_f32_e32 v72, v72
	v_exp_f32_e32 v73, v73
	v_lshlrev_b32_e32 v76, 16, v240
	v_and_b32_e32 v77, 0xffff0000, v240
	v_add_f32_e32 v72, 1.0, v72
	v_add_f32_e32 v73, 1.0, v73
	v_rcp_f32_e32 v72, v72
	v_rcp_f32_e32 v73, v73
	v_lshlrev_b32_e32 v74, 16, v241
	v_and_b32_e32 v75, 0xffff0000, v241
	v_pk_fma_f32 v[72:73], v[64:65], v[72:73], v[76:77]
	v_mul_f32_e32 v64, 0xbfb8aa3b, v88
	v_mul_f32_e32 v65, 0xbfb8aa3b, v89
	v_exp_f32_e32 v64, v64
	v_exp_f32_e32 v65, v65
	v_add_f32_e32 v64, 1.0, v64
	v_add_f32_e32 v65, 1.0, v65
	v_rcp_f32_e32 v64, v64
	v_rcp_f32_e32 v65, v65
	s_nop 0
	v_pk_fma_f32 v[74:75], v[66:67], v[64:65], v[74:75]
	v_cvt_pk_bf16_f32 v64, v68, v69
	v_cvt_pk_bf16_f32 v65, v70, v71
	v_cvt_pk_bf16_f32 v66, v72, v73
	v_cvt_pk_bf16_f32 v67, v74, v75
	global_store_dwordx4 v[80:81], v[64:67], off offset:256
	s_mov_b64 s[92:93], 0x8dc1000
	v_lshl_add_u64 v[244:245], v[242:243], 0, s[92:93]
	global_load_dwordx4 v[178:181], v[244:245], off
	s_mov_b64 s[92:93], 0x40000
	v_lshl_add_u64 v[248:249], v[246:247], 0, s[92:93]
	global_load_dwordx4 v[182:185], v[248:249], off
	s_mov_b64 s[92:93], 0x8dc1100
	v_lshl_add_u64 v[244:245], v[242:243], 0, s[92:93]
	global_load_dwordx4 v[186:189], v[244:245], off
	s_mov_b64 s[92:93], 0x40100
	v_lshl_add_u64 v[248:249], v[246:247], 0, s[92:93]
	global_load_dwordx4 v[190:193], v[248:249], off
	s_mov_b64 s[92:93], 0x8dd9000
	v_lshl_add_u64 v[244:245], v[242:243], 0, s[92:93]
	global_load_dwordx4 v[194:197], v[244:245], off
	s_mov_b64 s[92:93], 0x48000
	v_lshl_add_u64 v[248:249], v[246:247], 0, s[92:93]
	global_load_dwordx4 v[198:201], v[248:249], off
	s_mov_b64 s[92:93], 0x8dd9100
	v_lshl_add_u64 v[244:245], v[242:243], 0, s[92:93]
	global_load_dwordx4 v[202:205], v[244:245], off
	s_mov_b64 s[92:93], 0x48100
	v_lshl_add_u64 v[248:249], v[246:247], 0, s[92:93]
	global_load_dwordx4 v[206:209], v[248:249], off
	s_mov_b64 s[92:93], 0x8df1000
	v_lshl_add_u64 v[244:245], v[242:243], 0, s[92:93]
	global_load_dwordx4 v[210:213], v[244:245], off
	s_mov_b64 s[92:93], 0x50000
	v_lshl_add_u64 v[248:249], v[246:247], 0, s[92:93]
	global_load_dwordx4 v[214:217], v[248:249], off
	s_mov_b64 s[92:93], 0x8df1100
	v_lshl_add_u64 v[244:245], v[242:243], 0, s[92:93]
	global_load_dwordx4 v[218:221], v[244:245], off
	s_mov_b64 s[92:93], 0x50100
	v_lshl_add_u64 v[248:249], v[246:247], 0, s[92:93]
	global_load_dwordx4 v[222:225], v[248:249], off
	s_mov_b64 s[92:93], 0x8e09000
	v_lshl_add_u64 v[244:245], v[242:243], 0, s[92:93]
	global_load_dwordx4 v[226:229], v[244:245], off
	s_mov_b64 s[92:93], 0x58000
	v_lshl_add_u64 v[248:249], v[246:247], 0, s[92:93]
	global_load_dwordx4 v[230:233], v[248:249], off
	s_mov_b64 s[92:93], 0x8e09100
	v_lshl_add_u64 v[244:245], v[242:243], 0, s[92:93]
	global_load_dwordx4 v[234:237], v[244:245], off
	s_mov_b64 s[92:93], 0x58100
	v_lshl_add_u64 v[248:249], v[246:247], 0, s[92:93]
	global_load_dwordx4 v[238:241], v[248:249], off
	s_mov_b64 s[0:1], 0x8dc1000
	v_lshl_add_u64 v[74:75], v[144:145], 0, s[0:1]
	v_lshl_add_u64 v[64:65], v[74:75], 0, v[130:131]
	s_mov_b32 s0, 0x40000
	v_add_co_u32_e32 v76, vcc, s0, v128
	s_mov_b64 s[26:27], 0x40000
	s_nop 0
	v_addc_co_u32_e32 v77, vcc, 0, v129, vcc
	v_lshl_add_u64 v[64:65], v[128:129], 0, s[26:27]
	s_waitcnt vmcnt(14)
	v_lshlrev_b32_e32 v78, 16, v178
	v_and_b32_e32 v79, 0xffff0000, v178
	v_lshlrev_b32_e32 v80, 16, v179
	v_and_b32_e32 v81, 0xffff0000, v179
	v_mul_f32_e32 v66, 0xbfb8aa3b, v78
	v_mul_f32_e32 v67, 0xbfb8aa3b, v79
	v_exp_f32_e32 v66, v66
	v_exp_f32_e32 v67, v67
	v_lshlrev_b32_e32 v82, 16, v180
	v_and_b32_e32 v83, 0xffff0000, v180
	v_add_f32_e32 v66, 1.0, v66
	v_add_f32_e32 v67, 1.0, v67
	v_rcp_f32_e32 v66, v66
	v_rcp_f32_e32 v67, v67
	v_lshlrev_b32_e32 v84, 16, v181
	v_and_b32_e32 v85, 0xffff0000, v181
	s_waitcnt vmcnt(14)
	v_lshlrev_b32_e32 v68, 16, v182
	v_and_b32_e32 v69, 0xffff0000, v182
	v_pk_fma_f32 v[60:61], v[60:61], v[66:67], v[68:69]
	v_mul_f32_e32 v66, 0xbfb8aa3b, v80
	v_mul_f32_e32 v67, 0xbfb8aa3b, v81
	v_exp_f32_e32 v66, v66
	v_exp_f32_e32 v67, v67
	v_lshlrev_b32_e32 v68, 16, v183
	v_and_b32_e32 v69, 0xffff0000, v183
	v_add_f32_e32 v66, 1.0, v66
	v_add_f32_e32 v67, 1.0, v67
	v_rcp_f32_e32 v66, v66
	v_rcp_f32_e32 v67, v67
	s_nop 0
	v_pk_fma_f32 v[62:63], v[62:63], v[66:67], v[68:69]
	v_mul_f32_e32 v66, 0xbfb8aa3b, v82
	v_mul_f32_e32 v67, 0xbfb8aa3b, v83
	v_exp_f32_e32 v66, v66
	v_exp_f32_e32 v67, v67
	v_lshlrev_b32_e32 v68, 16, v184
	v_and_b32_e32 v69, 0xffff0000, v184
	v_add_f32_e32 v66, 1.0, v66
	v_add_f32_e32 v67, 1.0, v67
	v_rcp_f32_e32 v66, v66
	v_rcp_f32_e32 v67, v67
	s_nop 0
	v_pk_fma_f32 v[66:67], v[56:57], v[66:67], v[68:69]
	v_mul_f32_e32 v56, 0xbfb8aa3b, v84
	v_mul_f32_e32 v57, 0xbfb8aa3b, v85
	v_exp_f32_e32 v56, v56
	v_exp_f32_e32 v57, v57
	v_lshlrev_b32_e32 v68, 16, v185
	v_and_b32_e32 v69, 0xffff0000, v185
	v_add_f32_e32 v56, 1.0, v56
	v_add_f32_e32 v57, 1.0, v57
	v_rcp_f32_e32 v56, v56
	v_rcp_f32_e32 v57, v57
	s_nop 0
	v_pk_fma_f32 v[68:69], v[58:59], v[56:57], v[68:69]
	v_cvt_pk_bf16_f32 v56, v60, v61
	v_cvt_pk_bf16_f32 v57, v62, v63
	v_cvt_pk_bf16_f32 v58, v66, v67
	v_cvt_pk_bf16_f32 v59, v68, v69
	global_store_dwordx4 v[76:77], v[56:59], off
	s_nop 1
	v_lshl_add_u64 v[56:57], v[74:75], 0, v[124:125]
	s_nop 0
	s_waitcnt vmcnt(13)
	v_lshlrev_b32_e32 v66, 16, v186
	v_and_b32_e32 v67, 0xffff0000, v186
	v_lshlrev_b32_e32 v68, 16, v187
	v_and_b32_e32 v69, 0xffff0000, v187
	v_mul_f32_e32 v60, 0xbfb8aa3b, v66
	v_mul_f32_e32 v61, 0xbfb8aa3b, v67
	v_exp_f32_e32 v60, v60
	v_exp_f32_e32 v61, v61
	v_lshlrev_b32_e32 v70, 16, v188
	v_and_b32_e32 v71, 0xffff0000, v188
	v_lshlrev_b32_e32 v72, 16, v189
	v_and_b32_e32 v73, 0xffff0000, v189
	s_waitcnt vmcnt(13)
	v_lshlrev_b32_e32 v62, 16, v190
	v_and_b32_e32 v63, 0xffff0000, v190
	v_mul_f32_e32 v56, 0xbfb8aa3b, v68
	v_add_f32_e32 v60, 1.0, v60
	v_add_f32_e32 v61, 1.0, v61
	v_exp_f32_e32 v56, v56
	v_rcp_f32_e32 v60, v60
	v_rcp_f32_e32 v61, v61
	v_add_f32_e32 v56, 1.0, v56
	v_pk_fma_f32 v[52:53], v[52:53], v[60:61], v[62:63]
	v_rcp_f32_e32 v60, v56
	v_mul_f32_e32 v56, 0xbfb8aa3b, v69
	v_exp_f32_e32 v56, v56
	s_nop 0
	v_add_f32_e32 v56, 1.0, v56
	v_rcp_f32_e32 v61, v56
	v_lshlrev_b32_e32 v56, 16, v191
	v_and_b32_e32 v57, 0xffff0000, v191
	v_pk_fma_f32 v[54:55], v[54:55], v[60:61], v[56:57]
	v_mul_f32_e32 v56, 0xbfb8aa3b, v70
	v_mul_f32_e32 v57, 0xbfb8aa3b, v71
	v_exp_f32_e32 v56, v56
	v_exp_f32_e32 v57, v57
	v_lshlrev_b32_e32 v60, 16, v192
	v_and_b32_e32 v61, 0xffff0000, v192
	v_add_f32_e32 v56, 1.0, v56
	v_add_f32_e32 v57, 1.0, v57
	v_rcp_f32_e32 v56, v56
	v_rcp_f32_e32 v57, v57
	v_lshlrev_b32_e32 v58, 16, v193
	v_and_b32_e32 v59, 0xffff0000, v193
	v_pk_fma_f32 v[56:57], v[48:49], v[56:57], v[60:61]
	v_mul_f32_e32 v48, 0xbfb8aa3b, v72
	v_mul_f32_e32 v49, 0xbfb8aa3b, v73
	v_exp_f32_e32 v48, v48
	v_exp_f32_e32 v49, v49
	v_add_f32_e32 v48, 1.0, v48
	v_add_f32_e32 v49, 1.0, v49
	v_rcp_f32_e32 v48, v48
	v_rcp_f32_e32 v49, v49
	s_nop 0
	v_pk_fma_f32 v[58:59], v[50:51], v[48:49], v[58:59]
	v_cvt_pk_bf16_f32 v48, v52, v53
	v_cvt_pk_bf16_f32 v49, v54, v55
	v_cvt_pk_bf16_f32 v50, v56, v57
	v_cvt_pk_bf16_f32 v51, v58, v59
	global_store_dwordx4 v[64:65], v[48:51], off offset:256
	s_mov_b64 s[0:1], 0x90
	s_nop 0
	v_lshl_add_u64 v[50:51], v[132:133], 0, s[0:1]
	v_mad_i64_i32 v[48:49], s[0:1], v50, s6, v[134:135]
	v_lshl_add_u64 v[52:53], v[48:49], 0, s[12:13]
	v_lshl_add_u64 v[54:55], v[52:53], 0, v[130:131]
	v_lshlrev_b64 v[50:51], 11, v[50:51]
	v_lshl_add_u64 v[50:51], s[4:5], 0, v[50:51]
	v_lshl_add_u64 v[50:51], v[50:51], 0, v[130:131]
	s_waitcnt vmcnt(12)
	v_lshlrev_b32_e32 v62, 16, v194
	v_and_b32_e32 v63, 0xffff0000, v194
	v_lshlrev_b32_e32 v64, 16, v195
	v_and_b32_e32 v65, 0xffff0000, v195
	v_mul_f32_e32 v54, 0xbfb8aa3b, v62
	v_mul_f32_e32 v55, 0xbfb8aa3b, v63
	v_exp_f32_e32 v54, v54
	v_exp_f32_e32 v55, v55
	v_lshlrev_b32_e32 v66, 16, v196
	v_and_b32_e32 v67, 0xffff0000, v196
	v_add_f32_e32 v54, 1.0, v54
	v_add_f32_e32 v55, 1.0, v55
	v_rcp_f32_e32 v54, v54
	v_rcp_f32_e32 v55, v55
	v_lshlrev_b32_e32 v68, 16, v197
	v_and_b32_e32 v69, 0xffff0000, v197
	s_waitcnt vmcnt(12)
	v_lshlrev_b32_e32 v56, 16, v198
	v_and_b32_e32 v57, 0xffff0000, v198
	v_pk_fma_f32 v[44:45], v[44:45], v[54:55], v[56:57]
	v_mul_f32_e32 v54, 0xbfb8aa3b, v64
	v_mul_f32_e32 v55, 0xbfb8aa3b, v65
	v_exp_f32_e32 v54, v54
	v_exp_f32_e32 v55, v55
	v_lshlrev_b32_e32 v56, 16, v199
	v_and_b32_e32 v57, 0xffff0000, v199
	v_add_f32_e32 v54, 1.0, v54
	v_add_f32_e32 v55, 1.0, v55
	v_rcp_f32_e32 v54, v54
	v_rcp_f32_e32 v55, v55
	s_nop 0
	v_pk_fma_f32 v[46:47], v[46:47], v[54:55], v[56:57]
	v_mul_f32_e32 v54, 0xbfb8aa3b, v66
	v_mul_f32_e32 v55, 0xbfb8aa3b, v67
	v_exp_f32_e32 v54, v54
	v_exp_f32_e32 v55, v55
	v_lshlrev_b32_e32 v56, 16, v200
	v_and_b32_e32 v57, 0xffff0000, v200
	v_add_f32_e32 v54, 1.0, v54
	v_add_f32_e32 v55, 1.0, v55
	v_rcp_f32_e32 v54, v54
	v_rcp_f32_e32 v55, v55
	s_nop 0
	v_pk_fma_f32 v[54:55], v[40:41], v[54:55], v[56:57]
	v_mul_f32_e32 v40, 0xbfb8aa3b, v68
	v_mul_f32_e32 v41, 0xbfb8aa3b, v69
	v_exp_f32_e32 v40, v40
	v_exp_f32_e32 v41, v41
	v_lshlrev_b32_e32 v56, 16, v201
	v_and_b32_e32 v57, 0xffff0000, v201
	v_add_f32_e32 v40, 1.0, v40
	v_add_f32_e32 v41, 1.0, v41
	v_rcp_f32_e32 v40, v40
	v_rcp_f32_e32 v41, v41
	s_nop 0
	v_pk_fma_f32 v[56:57], v[42:43], v[40:41], v[56:57]
	v_cvt_pk_bf16_f32 v40, v44, v45
	v_cvt_pk_bf16_f32 v41, v46, v47
	v_cvt_pk_bf16_f32 v42, v54, v55
	v_cvt_pk_bf16_f32 v43, v56, v57
	global_store_dwordx4 v[50:51], v[40:43], off
	s_nop 1
	v_lshl_add_u64 v[40:41], v[52:53], 0, v[124:125]
	s_nop 0
	s_waitcnt vmcnt(11)
	v_lshlrev_b32_e32 v52, 16, v202
	v_and_b32_e32 v53, 0xffff0000, v202
	v_lshlrev_b32_e32 v54, 16, v203
	v_and_b32_e32 v55, 0xffff0000, v203
	v_mul_f32_e32 v44, 0xbfb8aa3b, v52
	v_mul_f32_e32 v45, 0xbfb8aa3b, v53
	v_exp_f32_e32 v44, v44
	v_exp_f32_e32 v45, v45
	v_lshlrev_b32_e32 v56, 16, v204
	v_and_b32_e32 v57, 0xffff0000, v204
	v_lshlrev_b32_e32 v58, 16, v205
	v_and_b32_e32 v59, 0xffff0000, v205
	s_waitcnt vmcnt(11)
	v_lshlrev_b32_e32 v46, 16, v206
	v_and_b32_e32 v47, 0xffff0000, v206
	v_mul_f32_e32 v40, 0xbfb8aa3b, v54
	v_add_f32_e32 v44, 1.0, v44
	v_add_f32_e32 v45, 1.0, v45
	v_exp_f32_e32 v40, v40
	v_rcp_f32_e32 v44, v44
	v_rcp_f32_e32 v45, v45
	v_add_f32_e32 v40, 1.0, v40
	v_pk_fma_f32 v[36:37], v[36:37], v[44:45], v[46:47]
	v_rcp_f32_e32 v44, v40
	v_mul_f32_e32 v40, 0xbfb8aa3b, v55
	v_exp_f32_e32 v40, v40
	s_nop 0
	v_add_f32_e32 v40, 1.0, v40
	v_rcp_f32_e32 v45, v40
	v_lshlrev_b32_e32 v40, 16, v207
	v_and_b32_e32 v41, 0xffff0000, v207
	v_pk_fma_f32 v[38:39], v[38:39], v[44:45], v[40:41]
	v_mul_f32_e32 v40, 0xbfb8aa3b, v56
	v_mul_f32_e32 v41, 0xbfb8aa3b, v57
	v_exp_f32_e32 v40, v40
	v_exp_f32_e32 v41, v41
	v_lshlrev_b32_e32 v44, 16, v208
	v_and_b32_e32 v45, 0xffff0000, v208
	v_add_f32_e32 v40, 1.0, v40
	v_add_f32_e32 v41, 1.0, v41
	v_rcp_f32_e32 v40, v40
	v_rcp_f32_e32 v41, v41
	v_lshlrev_b32_e32 v42, 16, v209
	v_and_b32_e32 v43, 0xffff0000, v209
	v_pk_fma_f32 v[40:41], v[32:33], v[40:41], v[44:45]
	v_mul_f32_e32 v32, 0xbfb8aa3b, v58
	v_mul_f32_e32 v33, 0xbfb8aa3b, v59
	v_exp_f32_e32 v32, v32
	v_exp_f32_e32 v33, v33
	v_add_f32_e32 v32, 1.0, v32
	v_add_f32_e32 v33, 1.0, v33
	v_rcp_f32_e32 v32, v32
	v_rcp_f32_e32 v33, v33
	s_nop 0
	v_pk_fma_f32 v[42:43], v[34:35], v[32:33], v[42:43]
	v_cvt_pk_bf16_f32 v32, v36, v37
	v_cvt_pk_bf16_f32 v33, v38, v39
	v_cvt_pk_bf16_f32 v34, v40, v41
	v_cvt_pk_bf16_f32 v35, v42, v43
	global_store_dwordx4 v[50:51], v[32:35], off offset:256
	v_lshl_add_u64 v[42:43], v[48:49], 0, s[14:15]
	s_nop 0
	v_lshl_add_u64 v[32:33], v[42:43], 0, v[130:131]
	s_mov_b64 s[0:1], 0x50000
	v_lshl_add_u64 v[32:33], v[128:129], 0, s[0:1]
	s_mov_b32 s0, 0x50000
	v_add_co_u32_e32 v44, vcc, s0, v128
	s_waitcnt vmcnt(10)
	v_lshlrev_b32_e32 v46, 16, v210
	v_addc_co_u32_e32 v45, vcc, 0, v129, vcc
	v_and_b32_e32 v47, 0xffff0000, v210
	v_lshlrev_b32_e32 v50, 16, v211
	v_and_b32_e32 v51, 0xffff0000, v211
	v_mul_f32_e32 v34, 0xbfb8aa3b, v46
	v_mul_f32_e32 v35, 0xbfb8aa3b, v47
	v_exp_f32_e32 v34, v34
	v_exp_f32_e32 v35, v35
	v_lshlrev_b32_e32 v52, 16, v212
	v_and_b32_e32 v53, 0xffff0000, v212
	v_add_f32_e32 v34, 1.0, v34
	v_add_f32_e32 v35, 1.0, v35
	v_rcp_f32_e32 v34, v34
	v_rcp_f32_e32 v35, v35
	v_lshlrev_b32_e32 v54, 16, v213
	v_and_b32_e32 v55, 0xffff0000, v213
	s_waitcnt vmcnt(10)
	v_lshlrev_b32_e32 v36, 16, v214
	v_and_b32_e32 v37, 0xffff0000, v214
	v_pk_fma_f32 v[28:29], v[28:29], v[34:35], v[36:37]
	v_mul_f32_e32 v34, 0xbfb8aa3b, v50
	v_mul_f32_e32 v35, 0xbfb8aa3b, v51
	v_exp_f32_e32 v34, v34
	v_exp_f32_e32 v35, v35
	v_lshlrev_b32_e32 v36, 16, v215
	v_and_b32_e32 v37, 0xffff0000, v215
	v_add_f32_e32 v34, 1.0, v34
	v_add_f32_e32 v35, 1.0, v35
	v_rcp_f32_e32 v34, v34
	v_rcp_f32_e32 v35, v35
	s_nop 0
	v_pk_fma_f32 v[30:31], v[30:31], v[34:35], v[36:37]
	v_mul_f32_e32 v34, 0xbfb8aa3b, v52
	v_mul_f32_e32 v35, 0xbfb8aa3b, v53
	v_exp_f32_e32 v34, v34
	v_exp_f32_e32 v35, v35
	v_lshlrev_b32_e32 v36, 16, v216
	v_and_b32_e32 v37, 0xffff0000, v216
	v_add_f32_e32 v34, 1.0, v34
	v_add_f32_e32 v35, 1.0, v35
	v_rcp_f32_e32 v34, v34
	v_rcp_f32_e32 v35, v35
	s_nop 0
	v_pk_fma_f32 v[34:35], v[24:25], v[34:35], v[36:37]
	v_mul_f32_e32 v24, 0xbfb8aa3b, v54
	v_mul_f32_e32 v25, 0xbfb8aa3b, v55
	v_exp_f32_e32 v24, v24
	v_exp_f32_e32 v25, v25
	v_lshlrev_b32_e32 v36, 16, v217
	v_and_b32_e32 v37, 0xffff0000, v217
	v_add_f32_e32 v24, 1.0, v24
	v_add_f32_e32 v25, 1.0, v25
	v_rcp_f32_e32 v24, v24
	v_rcp_f32_e32 v25, v25
	s_nop 0
	v_pk_fma_f32 v[36:37], v[26:27], v[24:25], v[36:37]
	v_cvt_pk_bf16_f32 v24, v28, v29
	v_cvt_pk_bf16_f32 v25, v30, v31
	v_cvt_pk_bf16_f32 v26, v34, v35
	v_cvt_pk_bf16_f32 v27, v36, v37
	global_store_dwordx4 v[44:45], v[24:27], off
	s_nop 1
	v_lshl_add_u64 v[24:25], v[42:43], 0, v[124:125]
	s_nop 0
	s_waitcnt vmcnt(9)
	v_lshlrev_b32_e32 v34, 16, v218
	v_and_b32_e32 v35, 0xffff0000, v218
	v_lshlrev_b32_e32 v36, 16, v219
	v_and_b32_e32 v37, 0xffff0000, v219
	v_mul_f32_e32 v28, 0xbfb8aa3b, v34
	v_mul_f32_e32 v29, 0xbfb8aa3b, v35
	v_exp_f32_e32 v28, v28
	v_exp_f32_e32 v29, v29
	v_lshlrev_b32_e32 v38, 16, v220
	v_and_b32_e32 v39, 0xffff0000, v220
	v_lshlrev_b32_e32 v40, 16, v221
	v_and_b32_e32 v41, 0xffff0000, v221
	s_waitcnt vmcnt(9)
	v_lshlrev_b32_e32 v30, 16, v222
	v_and_b32_e32 v31, 0xffff0000, v222
	v_mul_f32_e32 v24, 0xbfb8aa3b, v36
	v_add_f32_e32 v28, 1.0, v28
	v_add_f32_e32 v29, 1.0, v29
	v_exp_f32_e32 v24, v24
	v_rcp_f32_e32 v28, v28
	v_rcp_f32_e32 v29, v29
	v_add_f32_e32 v24, 1.0, v24
	v_pk_fma_f32 v[20:21], v[20:21], v[28:29], v[30:31]
	v_rcp_f32_e32 v28, v24
	v_mul_f32_e32 v24, 0xbfb8aa3b, v37
	v_exp_f32_e32 v24, v24
	s_nop 0
	v_add_f32_e32 v24, 1.0, v24
	v_rcp_f32_e32 v29, v24
	v_lshlrev_b32_e32 v24, 16, v223
	v_and_b32_e32 v25, 0xffff0000, v223
	v_pk_fma_f32 v[22:23], v[22:23], v[28:29], v[24:25]
	v_mul_f32_e32 v24, 0xbfb8aa3b, v38
	v_mul_f32_e32 v25, 0xbfb8aa3b, v39
	v_exp_f32_e32 v24, v24
	v_exp_f32_e32 v25, v25
	v_lshlrev_b32_e32 v28, 16, v224
	v_and_b32_e32 v29, 0xffff0000, v224
	v_add_f32_e32 v24, 1.0, v24
	v_add_f32_e32 v25, 1.0, v25
	v_rcp_f32_e32 v24, v24
	v_rcp_f32_e32 v25, v25
	v_lshlrev_b32_e32 v26, 16, v225
	v_and_b32_e32 v27, 0xffff0000, v225
	v_pk_fma_f32 v[24:25], v[16:17], v[24:25], v[28:29]
	v_mul_f32_e32 v16, 0xbfb8aa3b, v40
	v_mul_f32_e32 v17, 0xbfb8aa3b, v41
	v_exp_f32_e32 v16, v16
	v_exp_f32_e32 v17, v17
	v_add_f32_e32 v16, 1.0, v16
	v_add_f32_e32 v17, 1.0, v17
	v_rcp_f32_e32 v16, v16
	v_rcp_f32_e32 v17, v17
	s_nop 0
	v_pk_fma_f32 v[26:27], v[18:19], v[16:17], v[26:27]
	v_cvt_pk_bf16_f32 v16, v20, v21
	v_cvt_pk_bf16_f32 v17, v22, v23
	v_cvt_pk_bf16_f32 v18, v24, v25
	v_cvt_pk_bf16_f32 v19, v26, v27
	global_store_dwordx4 v[32:33], v[16:19], off offset:256
	v_lshl_add_u64 v[26:27], v[48:49], 0, s[36:37]
	s_nop 0
	v_lshl_add_u64 v[16:17], v[26:27], 0, v[130:131]
	s_mov_b64 s[0:1], 0x58000
	v_lshl_add_u64 v[16:17], v[128:129], 0, s[0:1]
	s_mov_b32 s0, 0x58000
	v_add_co_u32_e32 v28, vcc, s0, v128
	s_waitcnt vmcnt(8)
	v_lshlrev_b32_e32 v30, 16, v226
	v_addc_co_u32_e32 v29, vcc, 0, v129, vcc
	v_and_b32_e32 v31, 0xffff0000, v226
	v_lshlrev_b32_e32 v32, 16, v227
	v_and_b32_e32 v33, 0xffff0000, v227
	v_mul_f32_e32 v18, 0xbfb8aa3b, v30
	v_mul_f32_e32 v19, 0xbfb8aa3b, v31
	v_exp_f32_e32 v18, v18
	v_exp_f32_e32 v19, v19
	v_lshlrev_b32_e32 v34, 16, v228
	v_and_b32_e32 v35, 0xffff0000, v228
	v_add_f32_e32 v18, 1.0, v18
	v_add_f32_e32 v19, 1.0, v19
	v_rcp_f32_e32 v18, v18
	v_rcp_f32_e32 v19, v19
	v_lshlrev_b32_e32 v36, 16, v229
	v_and_b32_e32 v37, 0xffff0000, v229
	s_waitcnt vmcnt(8)
	v_lshlrev_b32_e32 v20, 16, v230
	v_and_b32_e32 v21, 0xffff0000, v230
	v_pk_fma_f32 v[12:13], v[12:13], v[18:19], v[20:21]
	v_mul_f32_e32 v18, 0xbfb8aa3b, v32
	v_mul_f32_e32 v19, 0xbfb8aa3b, v33
	v_exp_f32_e32 v18, v18
	v_exp_f32_e32 v19, v19
	v_lshlrev_b32_e32 v20, 16, v231
	v_and_b32_e32 v21, 0xffff0000, v231
	v_add_f32_e32 v18, 1.0, v18
	v_add_f32_e32 v19, 1.0, v19
	v_rcp_f32_e32 v18, v18
	v_rcp_f32_e32 v19, v19
	s_nop 0
	v_pk_fma_f32 v[14:15], v[14:15], v[18:19], v[20:21]
	v_mul_f32_e32 v18, 0xbfb8aa3b, v34
	v_mul_f32_e32 v19, 0xbfb8aa3b, v35
	v_exp_f32_e32 v18, v18
	v_exp_f32_e32 v19, v19
	v_lshlrev_b32_e32 v20, 16, v232
	v_and_b32_e32 v21, 0xffff0000, v232
	v_add_f32_e32 v18, 1.0, v18
	v_add_f32_e32 v19, 1.0, v19
	v_rcp_f32_e32 v18, v18
	v_rcp_f32_e32 v19, v19
	s_nop 0
	v_pk_fma_f32 v[18:19], v[8:9], v[18:19], v[20:21]
	v_mul_f32_e32 v8, 0xbfb8aa3b, v36
	v_mul_f32_e32 v9, 0xbfb8aa3b, v37
	v_exp_f32_e32 v8, v8
	v_exp_f32_e32 v9, v9
	v_lshlrev_b32_e32 v20, 16, v233
	v_and_b32_e32 v21, 0xffff0000, v233
	v_add_f32_e32 v8, 1.0, v8
	v_add_f32_e32 v9, 1.0, v9
	v_rcp_f32_e32 v8, v8
	v_rcp_f32_e32 v9, v9
	s_nop 0
	v_pk_fma_f32 v[20:21], v[10:11], v[8:9], v[20:21]
	v_cvt_pk_bf16_f32 v8, v12, v13
	v_cvt_pk_bf16_f32 v9, v14, v15
	v_cvt_pk_bf16_f32 v10, v18, v19
	v_cvt_pk_bf16_f32 v11, v20, v21
	global_store_dwordx4 v[28:29], v[8:11], off
	s_nop 1
	v_lshl_add_u64 v[8:9], v[26:27], 0, v[124:125]
	s_nop 0
	s_waitcnt vmcnt(7)
	v_lshlrev_b32_e32 v18, 16, v234
	v_and_b32_e32 v19, 0xffff0000, v234
	v_lshlrev_b32_e32 v20, 16, v235
	v_and_b32_e32 v21, 0xffff0000, v235
	v_mul_f32_e32 v12, 0xbfb8aa3b, v18
	v_mul_f32_e32 v13, 0xbfb8aa3b, v19
	v_exp_f32_e32 v12, v12
	v_exp_f32_e32 v13, v13
	v_lshlrev_b32_e32 v22, 16, v236
	v_and_b32_e32 v23, 0xffff0000, v236
	v_lshlrev_b32_e32 v24, 16, v237
	v_and_b32_e32 v25, 0xffff0000, v237
	s_waitcnt vmcnt(7)
	v_lshlrev_b32_e32 v14, 16, v238
	v_and_b32_e32 v15, 0xffff0000, v238
	v_mul_f32_e32 v8, 0xbfb8aa3b, v20
	v_add_f32_e32 v12, 1.0, v12
	v_add_f32_e32 v13, 1.0, v13
	v_exp_f32_e32 v8, v8
	v_rcp_f32_e32 v12, v12
	v_rcp_f32_e32 v13, v13
	v_add_f32_e32 v8, 1.0, v8
	v_pk_fma_f32 v[4:5], v[4:5], v[12:13], v[14:15]
	v_rcp_f32_e32 v12, v8
	v_mul_f32_e32 v8, 0xbfb8aa3b, v21
	v_exp_f32_e32 v8, v8
	s_nop 0
	v_add_f32_e32 v8, 1.0, v8
	v_rcp_f32_e32 v13, v8
	v_lshlrev_b32_e32 v8, 16, v239
	v_and_b32_e32 v9, 0xffff0000, v239
	v_pk_fma_f32 v[6:7], v[6:7], v[12:13], v[8:9]
	v_mul_f32_e32 v8, 0xbfb8aa3b, v22
	v_mul_f32_e32 v9, 0xbfb8aa3b, v23
	v_exp_f32_e32 v8, v8
	v_exp_f32_e32 v9, v9
	v_lshlrev_b32_e32 v12, 16, v240
	v_and_b32_e32 v13, 0xffff0000, v240
	v_add_f32_e32 v8, 1.0, v8
	v_add_f32_e32 v9, 1.0, v9
	v_rcp_f32_e32 v8, v8
	v_rcp_f32_e32 v9, v9
	v_lshlrev_b32_e32 v10, 16, v241
	v_and_b32_e32 v11, 0xffff0000, v241
	v_pk_fma_f32 v[8:9], v[0:1], v[8:9], v[12:13]
	v_mul_f32_e32 v0, 0xbfb8aa3b, v24
	v_mul_f32_e32 v1, 0xbfb8aa3b, v25
	v_exp_f32_e32 v0, v0
	v_exp_f32_e32 v1, v1
	v_add_f32_e32 v0, 1.0, v0
	v_add_f32_e32 v1, 1.0, v1
	v_rcp_f32_e32 v0, v0
	v_rcp_f32_e32 v1, v1
	s_nop 0
	v_pk_fma_f32 v[10:11], v[2:3], v[0:1], v[10:11]
	v_cvt_pk_bf16_f32 v0, v4, v5
	v_cvt_pk_bf16_f32 v1, v6, v7
	v_cvt_pk_bf16_f32 v2, v8, v9
	v_cvt_pk_bf16_f32 v3, v10, v11
	global_store_dwordx4 v[16:17], v[0:3], off offset:256
	s_add_i32 s8, s8, s74
	s_add_i32 s11, s11, s20
	s_cmpk_lt_i32 s8, 0x100
	s_cbranch_scc0 .LBB0_555
